# select phase: serpentine item assignment so all workgroups process the same number of key tiles
# speedup vs baseline: 1.0028x; 1.0028x over previous
; DI int opaque_tid() { int t = threadIdx.x; asm volatile("" : "+v"(t)); return t; }
; DI void select_item(const Params& p, int item, char* smem) {
;   SelSmem* S = (SelSmem*)smem;
;   const u16* PROJ = (const u16*)(p.ws + WS_PROJ);
;   uint32_t* BM = (uint32_t*)(p.ws + WS_BM);
;   const int b = item & 3, t0 = (1023 - (item >> 2)) * 4;
;   const int tokbase = b * 4096;
;   const int tid = opaque_tid(), lane = tid & 63, wave = __builtin_amdgcn_readfirstlane(tid >> 6), r = lane & 31, h = lane >> 5;
;   if (t0 + 3 < 256) {
;     if (tid < 32) {
;       const int q = tid >> 3, tile = tid & 7, t = t0 + q;
;       uint32_t wd = (tile < (t >> 5)) ? 0xffffffffu : (tile == (t >> 5) ? (0xffffffffu >> (31 - (t & 31))) : 0u);
;       BM[(size_t)(tokbase + t) * 128 + tile] = wd;
;     }
;     return;
;   }
;   const int ntiles = 2 * (t0 >> 6) + 2;
;   if (tid < 4) { S->need[tid] = 256u; S->pfx[tid] = 0u; S->dcut[tid] = 0u; }
; __global__ void __launch_bounds__(256, 2) hybrid_megakernel(Params p, int ph_lo, int ph_hi, int do_sync) {
;     ...
;         for (int it = bid; it < total; it += nb) {
;           if (it < 4096) select_item(p, it, smem);
.LBB0_358:
	s_andn2_b64 vcc, exec, s[0:1]
	s_cbranch_vccnz .LBB0_286
	s_bfe_u32 s0, s59, 0x10009
	s_sub_i32 s0, 0, s0
	s_and_b32 s0, s0, 0x1ff
	s_cmpk_eq_u32 s25, 0x200
	s_cselect_b32 s0, s0, 0
	s_xor_b32 s5, s59, s0
	s_lshl_b32 s30, s5, 12
	s_and_b32 s30, s30, 0x3000
	s_and_b32 s0, s5, -4
	s_sub_i32 s5, 0xffc, s0
	v_mov_b32_e32 v110, v128
	s_addk_i32 s0, 0xf000
	s_cmpk_lt_i32 s0, 0xff00
	v_readfirstlane_b32 s13, v110
	s_mov_b64 s[0:1], -1
	s_cbranch_scc0 .LBB0_1390
	v_cmp_gt_i32_e32 vcc, 4, v110
	s_and_saveexec_b64 s[0:1], vcc
	s_cbranch_execz .LBB0_362
	v_lshlrev_b32_e32 v0, 2, v110
	s_waitcnt lgkmcnt(0)
	v_add_u32_e32 v1, 0x8000, v0
	v_mov_b32_e32 v2, 0x100
	ds_write2_b32 v1, v3, v2 offset1:4
	ds_write_b32 v0, v3 offset:32800
